# scan pass 2: second trip takes chunk 63-w so all workgroups walk equal carry chains
# baseline (speedup 1.0000x reference)
; template <class T> __device__ __forceinline__ T ntload(const T* p) { return __builtin_nontemporal_load(p); }
; __device__ __forceinline__ void scan2_phase(const bf16_t* LA, const bf16_t* BT, bf16_t* GS, int sw, View vw) {
;     ...
;     for (int idx = gtid; idx < (vw.MR >> 6) * 512; idx += NT) {
;         const int quad = idx & 511, bq = (vw.row0 >> 6) + (idx >> 9), q = bq & 63, b = bq >> 6;
;         const size_t base = (size_t)bq * 64 * E + 4 * quad;
;         u32x2 lw[8], bw[8], gw[8];
; #pragma unroll
;         for (int i = 0; i < 8; ++i) { lw[i] = ntload((const u32x2*)(LA + base + (size_t)i * E)); bw[i] = ntload((const u32x2*)(BT + base + (size_t)i * E)); gw[i] = ntload((const u32x2*)(GS + base + (size_t)i * E)); }
.LBB0_641:
	v_mov_b32_e32 v180, v136
	v_mov_b32_e32 v181, v137
	s_cmp_lg_u32 s15, 0x8000
	s_cbranch_scc1 .Ls2b_keep
	s_cmp_lg_u32 s28, 0x4000
	s_cbranch_scc1 .Ls2b_keep
	v_ashrrev_i32_e32 v182, 9, v136
	v_sub_u32_e32 v183, 0x5f, v182
	v_cmp_gt_i32_e32 vcc, 32, v182
	v_and_b32_e32 v180, 0x1ff, v136
	s_nop 0
	v_cndmask_b32_e32 v182, v183, v182, vcc
	v_lshl_or_b32 v180, v182, 9, v180
	v_lshlrev_b32_e32 v181, 2, v180
.Ls2b_keep:
	v_ashrrev_i32_e32 v0, 9, v180
	v_add_u32_e32 v2, s29, v0
	v_ashrrev_i32_e32 v3, 31, v2
	v_lshlrev_b64 v[106:107], 18, v[2:3]
	v_lshlrev_b32_e32 v0, 3, v180
	s_movk_i32 s24, 0xff8
	v_and_or_b32 v4, v0, s24, v106
	v_mov_b32_e32 v5, v107
	v_lshl_add_u64 v[96:97], s[10:11], 0, v[4:5]
	s_movk_i32 s24, 0x2000
	v_add_co_u32_e32 v46, vcc, s24, v96
	v_lshl_add_u64 v[98:99], s[12:13], 0, v[4:5]
	s_nop 0
	v_addc_co_u32_e32 v47, vcc, 0, v97, vcc
	v_add_co_u32_e32 v48, vcc, s24, v98
	v_lshl_add_u64 v[4:5], s[16:17], 0, v[4:5]
	s_nop 0
	v_addc_co_u32_e32 v49, vcc, 0, v99, vcc
	v_add_co_u32_e32 v64, vcc, s24, v4
	s_movk_i32 s24, 0x4000
	s_nop 0
	v_addc_co_u32_e32 v65, vcc, 0, v5, vcc
	global_load_dwordx2 v[40:41], v[96:97], off nt
	global_load_dwordx2 v[38:39], v[98:99], off nt
	global_load_dwordx2 v[34:35], v[4:5], off nt
	global_load_dwordx2 v[56:57], v[46:47], off offset:-4096 nt
	global_load_dwordx2 v[58:59], v[46:47], off nt
	global_load_dwordx2 v[52:53], v[48:49], off offset:-4096 nt
	global_load_dwordx2 v[54:55], v[48:49], off nt
	s_nop 0
	global_load_dwordx2 v[46:47], v[64:65], off offset:-4096 nt
	global_load_dwordx2 v[48:49], v[64:65], off nt
	v_add_co_u32_e32 v64, vcc, s24, v96
	v_lshlrev_b32_e32 v0, 2, v181
	s_nop 0
	v_addc_co_u32_e32 v65, vcc, 0, v97, vcc
	v_add_co_u32_e32 v66, vcc, s24, v98
	v_and_b32_e32 v110, 63, v2
	s_nop 0
	v_addc_co_u32_e32 v67, vcc, 0, v99, vcc
	v_add_co_u32_e32 v82, vcc, s24, v4
	s_movk_i32 s24, 0x6000
	s_nop 0
	v_addc_co_u32_e32 v83, vcc, 0, v5, vcc
	global_load_dwordx2 v[74:75], v[64:65], off offset:-4096 nt
	global_load_dwordx2 v[78:79], v[64:65], off nt
	global_load_dwordx2 v[70:71], v[66:67], off offset:-4096 nt
	global_load_dwordx2 v[72:73], v[66:67], off nt
	s_nop 0
	global_load_dwordx2 v[64:65], v[82:83], off offset:-4096 nt
	global_load_dwordx2 v[66:67], v[82:83], off nt
	v_add_co_u32_e32 v82, vcc, s24, v96
	v_mov_b32_e32 v3, v1
	s_nop 0
	v_addc_co_u32_e32 v83, vcc, 0, v97, vcc
	v_add_co_u32_e32 v84, vcc, s24, v98
	v_and_b32_e32 v111, 0x1ff0, v0
	s_nop 0
	v_addc_co_u32_e32 v85, vcc, 0, v99, vcc
	v_add_co_u32_e32 v100, vcc, s24, v4
	s_movk_i32 s24, 0x7000
	s_nop 0
	v_addc_co_u32_e32 v101, vcc, 0, v5, vcc
	v_add_co_u32_e32 v96, vcc, s24, v96
	global_load_dwordx2 v[92:93], v[82:83], off offset:-4096 nt
	global_load_dwordx2 v[94:95], v[82:83], off nt
	global_load_dwordx2 v[86:87], v[84:85], off offset:-4096 nt
	global_load_dwordx2 v[88:89], v[84:85], off nt
	s_nop 0
	global_load_dwordx2 v[82:83], v[100:101], off offset:-4096 nt
	global_load_dwordx2 v[84:85], v[100:101], off nt
	v_addc_co_u32_e32 v97, vcc, 0, v97, vcc
	global_load_dwordx2 v[100:101], v[96:97], off nt
	v_add_co_u32_e32 v96, vcc, s24, v98
	v_mov_b32_e32 v0, v1
	s_nop 0
	v_addc_co_u32_e32 v97, vcc, 0, v99, vcc
	v_add_co_u32_e32 v4, vcc, 0x7000, v4
	global_load_dwordx2 v[98:99], v[96:97], off nt
	s_nop 0
	v_addc_co_u32_e32 v5, vcc, 0, v5, vcc
	global_load_dwordx2 v[96:97], v[4:5], off nt
	v_and_b32_e32 v4, 0xffffffc0, v2
	v_ashrrev_i32_e32 v5, 31, v4
	v_mov_b32_e32 v2, v1
	v_lshlrev_b64 v[102:103], 13, v[4:5]
	v_mov_b64_e32 v[4:5], v[2:3]
	v_cmp_lt_u32_e32 vcc, 7, v110
	v_mov_b32_e32 v108, 0
	v_mov_b64_e32 v[2:3], v[0:1]
	s_and_saveexec_b64 s[24:25], vcc
	s_cbranch_execz .LBB0_645
	v_or_b32_e32 v2, v102, v111
	v_mov_b32_e32 v3, v103
	v_lshl_add_u64 v[104:105], s[18:19], 0, v[2:3]
	v_mov_b32_e32 v2, 0
	s_mov_b32 s31, 0
	s_mov_b64 s[26:27], 0
	v_mov_b32_e32 v3, v2
	v_mov_b32_e32 v4, v2
	v_mov_b32_e32 v5, v2
